# v10 + mout prologue loads batched (M1) + nt on attention O stores
# baseline (speedup 1.0000x reference)
.LBB0_254:
	s_add_i32 s2, s53, -1
	s_add_i32 s60, s52, s3
	s_and_b32 s50, s2, 1
	s_and_b32 s61, s53, 1
	s_and_b64 s[40:41], s[66:67], exec
	s_cselect_b32 s2, s50, s61
	s_mul_i32 s38, s2, 0x11000
	s_add_i32 s38, s38, s96
	s_and_b64 s[40:41], s[68:69], exec
	s_cselect_b32 s2, s50, s61
	s_mul_i32 s33, s2, 0x11000
	s_add_i32 s33, s33, s97
	v_add_u32_e32 v146, s38, v84
	v_lshlrev_b32_e32 v129, s48, v64
	s_and_b64 s[40:41], s[70:71], exec
	ds_read_b128 v[64:67], v146
	ds_read_b128 v[68:71], v146 offset:64
	ds_read_b128 v[130:133], v146 offset:128
	ds_read_b128 v[134:137], v146 offset:192
	ds_read_b128 v[138:141], v146 offset:1088
	ds_read_b128 v[142:145], v146 offset:1152
	ds_read_b128 v[148:151], v146 offset:1216
	ds_read_b128 v[152:155], v146 offset:1280
	v_add_u32_e32 v146, s33, v84
	s_cselect_b32 s2, s50, s61
	ds_read_b128 v[156:159], v146
	ds_read_b128 v[160:163], v146 offset:64
	ds_read_b128 v[164:167], v146 offset:128
	ds_read_b128 v[168:171], v146 offset:192
	ds_read_b128 v[172:175], v146 offset:1088
	ds_read_b128 v[176:179], v146 offset:1152
	ds_read_b128 v[184:187], v146 offset:1216
	ds_read_b128 v[188:191], v146 offset:1280
	s_mul_i32 s2, s2, 0x11000
	s_add_i32 s2, s2, s62
	s_and_b64 s[40:41], s[72:73], exec
	s_cselect_b32 s40, s50, s61
	s_mul_i32 s41, s40, 0x11000
	s_add_i32 s41, s41, s63
	s_and_b64 vcc, s[76:77], exec
	s_cselect_b32 s40, s50, s61
	s_mul_i32 s40, s40, 0x11000
	s_add_i32 s40, s40, s96
	s_waitcnt lgkmcnt(14)
	v_mfma_f32_16x16x32_bf16 v[64:67], v[64:67], v[48:51], 0
	v_mfma_f32_16x16x32_bf16 v[64:67], v[68:71], v[52:55], v[64:67]
	s_waitcnt lgkmcnt(11)
	v_mfma_f32_16x16x32_bf16 v[68:71], v[138:141], v[48:51], 0
	s_waitcnt lgkmcnt(10)
	v_mfma_f32_16x16x32_bf16 v[68:71], v[142:145], v[52:55], v[68:71]
	v_mfma_f32_16x16x32_bf16 v[64:67], v[130:133], v[56:59], v[64:67]
	s_waitcnt lgkmcnt(9)
	v_mfma_f32_16x16x32_bf16 v[68:71], v[148:151], v[56:59], v[68:71]
	v_mfma_f32_16x16x32_bf16 v[64:67], v[134:137], v[60:63], v[64:67]
	s_waitcnt lgkmcnt(8)
	v_mfma_f32_16x16x32_bf16 v[68:71], v[152:155], v[60:63], v[68:71]
	v_add_u32_e32 v146, s2, v84
	ds_read_b128 v[130:133], v146
	ds_read_b128 v[134:137], v146 offset:64
	ds_read_b128 v[138:141], v146 offset:128
	ds_read_b128 v[142:145], v146 offset:192
	ds_read_b128 v[148:151], v146 offset:1088
	ds_read_b128 v[152:155], v146 offset:1152
	ds_read_b128 v[192:195], v146 offset:1216
	ds_read_b128 v[196:199], v146 offset:1280
	s_waitcnt lgkmcnt(14)
	v_mfma_f32_16x16x32_bf16 v[156:159], v[156:159], v[48:51], 0
	v_mfma_f32_16x16x32_bf16 v[156:159], v[160:163], v[52:55], v[156:159]
	s_waitcnt lgkmcnt(11)
	v_mfma_f32_16x16x32_bf16 v[160:163], v[172:175], v[48:51], 0
	s_waitcnt lgkmcnt(10)
	v_mfma_f32_16x16x32_bf16 v[160:163], v[176:179], v[52:55], v[160:163]
	v_mfma_f32_16x16x32_bf16 v[156:159], v[164:167], v[56:59], v[156:159]
	s_waitcnt lgkmcnt(9)
	v_mfma_f32_16x16x32_bf16 v[160:163], v[184:187], v[56:59], v[160:163]
	v_mfma_f32_16x16x32_bf16 v[156:159], v[168:171], v[60:63], v[156:159]
	s_waitcnt lgkmcnt(8)
	v_mfma_f32_16x16x32_bf16 v[160:163], v[188:191], v[60:63], v[160:163]
	v_add_u32_e32 v146, s41, v84
	ds_read_b128 v[164:167], v146
	ds_read_b128 v[168:171], v146 offset:64
	ds_read_b128 v[172:175], v146 offset:128
	ds_read_b128 v[176:179], v146 offset:192
	ds_read_b128 v[184:187], v146 offset:1088
	ds_read_b128 v[188:191], v146 offset:1152
	ds_read_b128 v[200:203], v146 offset:1216
	ds_read_b128 v[204:207], v146 offset:1280
	s_waitcnt lgkmcnt(14)
	v_mfma_f32_16x16x32_bf16 v[130:133], v[130:133], v[48:51], 0
	v_mfma_f32_16x16x32_bf16 v[130:133], v[134:137], v[52:55], v[130:133]
	s_waitcnt lgkmcnt(11)
	v_mfma_f32_16x16x32_bf16 v[134:137], v[148:151], v[48:51], 0
	v_mfma_f32_16x16x32_bf16 v[130:133], v[138:141], v[56:59], v[130:133]
	s_waitcnt lgkmcnt(10)
	v_mfma_f32_16x16x32_bf16 v[134:137], v[152:155], v[52:55], v[134:137]
	v_mfma_f32_16x16x32_bf16 v[130:133], v[142:145], v[60:63], v[130:133]
	s_waitcnt lgkmcnt(9)
	v_mfma_f32_16x16x32_bf16 v[134:137], v[192:195], v[56:59], v[134:137]
	s_waitcnt lgkmcnt(8)
	v_mfma_f32_16x16x32_bf16 v[134:137], v[196:199], v[60:63], v[134:137]
	v_add_u32_e32 v146, s40, v84
	ds_read_b128 v[138:141], v146
	ds_read_b128 v[142:145], v146 offset:64
	ds_read_b128 v[148:151], v146 offset:128
	ds_read_b128 v[152:155], v146 offset:192
	ds_read_b128 v[192:195], v146 offset:1088
	ds_read_b128 v[196:199], v146 offset:1152
	ds_read_b128 v[208:211], v146 offset:1216
	ds_read_b128 v[212:215], v146 offset:1280
	s_waitcnt lgkmcnt(14)
	v_mfma_f32_16x16x32_bf16 v[164:167], v[164:167], v[48:51], 0
	v_mfma_f32_16x16x32_bf16 v[164:167], v[168:171], v[52:55], v[164:167]
	s_waitcnt lgkmcnt(11)
	v_mfma_f32_16x16x32_bf16 v[168:171], v[184:187], v[48:51], 0
	s_waitcnt lgkmcnt(10)
	v_mfma_f32_16x16x32_bf16 v[168:171], v[188:191], v[52:55], v[168:171]
	v_mfma_f32_16x16x32_bf16 v[164:167], v[172:175], v[56:59], v[164:167]
	s_waitcnt lgkmcnt(9)
	v_mfma_f32_16x16x32_bf16 v[168:171], v[200:203], v[56:59], v[168:171]
	v_mfma_f32_16x16x32_bf16 v[164:167], v[176:179], v[60:63], v[164:167]
	s_waitcnt lgkmcnt(8)
	v_mfma_f32_16x16x32_bf16 v[168:171], v[204:207], v[60:63], v[168:171]
	s_waitcnt lgkmcnt(7)
	v_mfma_f32_16x16x32_bf16 v[138:141], v[138:141], v[48:51], 0
	s_waitcnt lgkmcnt(3)
	v_mfma_f32_16x16x32_bf16 v[48:51], v[192:195], v[48:51], 0
	s_waitcnt lgkmcnt(2)
	v_mfma_f32_16x16x32_bf16 v[48:51], v[196:199], v[52:55], v[48:51]
	v_mfma_f32_16x16x32_bf16 v[138:141], v[142:145], v[52:55], v[138:141]
	s_waitcnt lgkmcnt(1)
	v_mfma_f32_16x16x32_bf16 v[48:51], v[208:211], v[56:59], v[48:51]
	v_mfma_f32_16x16x32_bf16 v[138:141], v[148:151], v[56:59], v[138:141]
	s_waitcnt lgkmcnt(0)
	v_mfma_f32_16x16x32_bf16 v[48:51], v[212:215], v[60:63], v[48:51]
	v_mfma_f32_16x16x32_bf16 v[138:141], v[152:155], v[60:63], v[138:141]
	s_cmp_lg_u32 s60, 0
	s_cselect_b64 s[92:93], -1, 0
	s_or_b64 s[60:61], s[92:93], s[78:79]
	v_fmamk_f32 v52, v64, 0x3e0293ee, v89
	s_and_b64 vcc, s[60:61], s[4:5]
	v_cndmask_b32_e32 v52, v82, v52, vcc
	v_fmamk_f32 v53, v65, 0x3e0293ee, v90
	s_and_b64 vcc, s[60:61], s[6:7]
	v_cndmask_b32_e32 v53, v82, v53, vcc
	v_fmamk_f32 v55, v66, 0x3e0293ee, v91
	s_and_b64 vcc, s[60:61], s[8:9]
	v_cndmask_b32_e32 v55, v82, v55, vcc
	v_fmamk_f32 v56, v67, 0x3e0293ee, v92
	s_and_b64 vcc, s[60:61], s[10:11]
	v_cndmask_b32_e32 v56, v82, v56, vcc
	v_fmamk_f32 v57, v68, 0x3e0293ee, v93
	s_and_b64 vcc, s[60:61], s[12:13]
	v_cndmask_b32_e32 v57, v82, v57, vcc
	v_fmamk_f32 v58, v69, 0x3e0293ee, v94
	s_and_b64 vcc, s[60:61], s[14:15]
	v_cndmask_b32_e32 v58, v82, v58, vcc
	v_fmamk_f32 v59, v70, 0x3e0293ee, v95
	s_and_b64 vcc, s[60:61], s[16:17]
	v_cndmask_b32_e32 v59, v82, v59, vcc
	v_fmamk_f32 v60, v71, 0x3e0293ee, v96
	s_and_b64 vcc, s[60:61], s[18:19]
	v_cndmask_b32_e32 v60, v82, v60, vcc
	v_fmamk_f32 v61, v156, 0x3e0293ee, v97
	s_or_b64 vcc, s[92:93], s[80:81]
	v_fmamk_f32 v62, v157, 0x3e0293ee, v98
	v_fmamk_f32 v63, v158, 0x3e0293ee, v99
	v_fmamk_f32 v64, v159, 0x3e0293ee, v100
	v_fmamk_f32 v65, v160, 0x3e0293ee, v101
	v_fmamk_f32 v66, v161, 0x3e0293ee, v102
	v_fmamk_f32 v67, v162, 0x3e0293ee, v103
	v_fmamk_f32 v68, v163, 0x3e0293ee, v104
	v_cndmask_b32_e32 v61, v82, v61, vcc
	v_cndmask_b32_e32 v62, v82, v62, vcc
	v_cndmask_b32_e32 v63, v82, v63, vcc
	v_cndmask_b32_e32 v64, v82, v64, vcc
	v_cndmask_b32_e32 v65, v82, v65, vcc
	v_cndmask_b32_e32 v66, v82, v66, vcc
	v_cndmask_b32_e32 v67, v82, v67, vcc
	v_cndmask_b32_e32 v68, v82, v68, vcc
	v_fmamk_f32 v69, v130, 0x3e0293ee, v105
	s_or_b64 vcc, s[92:93], s[82:83]
	v_fmamk_f32 v130, v133, 0x3e0293ee, v108
	v_fmamk_f32 v70, v131, 0x3e0293ee, v106
	v_cndmask_b32_e32 v131, v82, v130, vcc
	v_fmamk_f32 v130, v134, 0x3e0293ee, v109
	v_fmamk_f32 v71, v132, 0x3e0293ee, v107
	v_cndmask_b32_e32 v132, v82, v130, vcc
	v_fmamk_f32 v130, v135, 0x3e0293ee, v110
	v_max3_f32 v54, v52, s74, v53
	v_cndmask_b32_e32 v133, v82, v130, vcc
	v_fmamk_f32 v130, v136, 0x3e0293ee, v111
	v_max3_f32 v54, v54, v55, v56
	v_cndmask_b32_e32 v134, v82, v130, vcc
	v_fmamk_f32 v130, v137, 0x3e0293ee, v112
	v_max3_f32 v54, v54, v57, v58
	v_cndmask_b32_e32 v69, v82, v69, vcc
	v_cndmask_b32_e32 v70, v82, v70, vcc
	v_cndmask_b32_e32 v71, v82, v71, vcc
	v_cndmask_b32_e32 v135, v82, v130, vcc
	v_fmamk_f32 v130, v164, 0x3e0293ee, v113
	s_or_b64 vcc, s[92:93], s[84:85]
	v_max3_f32 v54, v54, v59, v60
	v_cndmask_b32_e32 v136, v82, v130, vcc
	v_fmamk_f32 v130, v165, 0x3e0293ee, v114
	v_max3_f32 v54, v54, v61, v62
	v_cndmask_b32_e32 v137, v82, v130, vcc
	v_fmamk_f32 v130, v166, 0x3e0293ee, v115
	v_max3_f32 v54, v54, v63, v64
	v_cndmask_b32_e32 v142, v82, v130, vcc
	v_fmamk_f32 v130, v167, 0x3e0293ee, v116
	v_max3_f32 v54, v54, v65, v66
	v_cndmask_b32_e32 v143, v82, v130, vcc
	v_fmamk_f32 v130, v168, 0x3e0293ee, v117
	v_max3_f32 v54, v54, v67, v68
	v_cndmask_b32_e32 v144, v82, v130, vcc
	v_fmamk_f32 v130, v169, 0x3e0293ee, v118
	v_max3_f32 v54, v54, v69, v70
	v_cndmask_b32_e32 v145, v82, v130, vcc
	v_fmamk_f32 v130, v170, 0x3e0293ee, v119
	v_max3_f32 v54, v54, v71, v131
	v_cndmask_b32_e32 v146, v82, v130, vcc
	v_fmamk_f32 v130, v171, 0x3e0293ee, v120
	s_or_b64 s[60:61], s[92:93], s[86:87]
	v_max3_f32 v54, v54, v132, v133
	v_cndmask_b32_e32 v147, v82, v130, vcc
	v_fmamk_f32 v130, v138, 0x3e0293ee, v121
	s_and_b64 vcc, s[60:61], s[20:21]
	v_max3_f32 v54, v54, v134, v135
	v_cndmask_b32_e32 v138, v82, v130, vcc
	v_fmamk_f32 v130, v139, 0x3e0293ee, v122
	s_and_b64 vcc, s[60:61], s[22:23]
	v_max3_f32 v54, v54, v136, v137
	v_cndmask_b32_e32 v139, v82, v130, vcc
	v_fmamk_f32 v130, v140, 0x3e0293ee, v123
	s_and_b64 vcc, s[60:61], s[24:25]
	v_max3_f32 v54, v54, v142, v143
	v_cndmask_b32_e32 v140, v82, v130, vcc
	v_fmamk_f32 v130, v141, 0x3e0293ee, v124
	s_and_b64 vcc, s[60:61], s[26:27]
	v_max3_f32 v54, v54, v144, v145
	v_cndmask_b32_e32 v141, v82, v130, vcc
	v_fmamk_f32 v48, v48, 0x3e0293ee, v125
	s_and_b64 vcc, s[60:61], s[28:29]
	v_max3_f32 v54, v54, v146, v147
	v_cndmask_b32_e32 v48, v82, v48, vcc
	v_fmamk_f32 v49, v49, 0x3e0293ee, v126
	s_and_b64 vcc, s[60:61], s[30:31]
	v_max3_f32 v54, v54, v138, v139
	v_cndmask_b32_e32 v49, v82, v49, vcc
	v_fmamk_f32 v50, v50, 0x3e0293ee, v127
	s_and_b64 vcc, s[60:61], s[34:35]
	v_max3_f32 v54, v54, v140, v141
	v_cndmask_b32_e32 v50, v82, v50, vcc
	v_fmamk_f32 v51, v51, 0x3e0293ee, v85
	s_and_b64 vcc, s[60:61], s[36:37]
	v_max3_f32 v54, v54, v48, v49
	v_cndmask_b32_e32 v51, v82, v51, vcc
	v_max3_f32 v54, v54, v50, v51
	ds_bpermute_b32 v130, v86, v54
	s_waitcnt lgkmcnt(0)
	v_max_f32_e32 v130, v130, v130
	v_max_f32_e32 v54, v54, v130
	ds_bpermute_b32 v130, v87, v54
	s_waitcnt lgkmcnt(0)
	v_max_f32_e32 v130, v130, v130
	v_max_f32_e32 v130, v54, v130
	v_sub_f32_e32 v52, v52, v130
	v_exp_f32_e32 v52, v52
	v_sub_f32_e32 v53, v53, v130
	v_exp_f32_e32 v53, v53
	v_sub_f32_e32 v54, v55, v130
	v_exp_f32_e32 v54, v54
	v_sub_f32_e32 v55, v56, v130
	v_exp_f32_e32 v55, v55
	v_sub_f32_e32 v57, v57, v130
	v_add_f32_e32 v56, 0, v52
	v_exp_f32_e32 v57, v57
	v_sub_f32_e32 v58, v58, v130
	v_add_f32_e32 v56, v53, v56
	v_exp_f32_e32 v58, v58
	v_sub_f32_e32 v59, v59, v130
	v_add_f32_e32 v56, v54, v56
	v_exp_f32_e32 v59, v59
	v_sub_f32_e32 v60, v60, v130
	v_add_f32_e32 v56, v55, v56
	v_exp_f32_e32 v60, v60
	v_sub_f32_e32 v61, v61, v130
	v_add_f32_e32 v56, v57, v56
	v_exp_f32_e32 v181, v61
	v_sub_f32_e32 v61, v62, v130
	v_add_f32_e32 v56, v58, v56
	v_exp_f32_e32 v183, v61
	v_sub_f32_e32 v61, v63, v130
	v_add_f32_e32 v56, v59, v56
	v_exp_f32_e32 v192, v61
	v_sub_f32_e32 v61, v64, v130
	v_add_f32_e32 v56, v60, v56
	v_exp_f32_e32 v193, v61
	v_sub_f32_e32 v61, v65, v130
	v_add_f32_e32 v56, v181, v56
	v_exp_f32_e32 v194, v61
	v_sub_f32_e32 v61, v66, v130
	v_add_f32_e32 v56, v183, v56
	v_exp_f32_e32 v195, v61
	v_sub_f32_e32 v61, v67, v130
	v_add_f32_e32 v56, v192, v56
	v_exp_f32_e32 v196, v61
	v_sub_f32_e32 v61, v68, v130
	v_add_f32_e32 v56, v193, v56
	v_exp_f32_e32 v197, v61
	v_sub_f32_e32 v61, v69, v130
	v_add_f32_e32 v56, v194, v56
	v_exp_f32_e32 v200, v61
	v_sub_f32_e32 v61, v70, v130
	v_add_f32_e32 v56, v195, v56
	v_exp_f32_e32 v201, v61
	v_sub_f32_e32 v61, v71, v130
	v_add_f32_e32 v56, v196, v56
	v_exp_f32_e32 v202, v61
	v_sub_f32_e32 v61, v131, v130
	v_add_f32_e32 v56, v197, v56
	v_exp_f32_e32 v203, v61
	v_sub_f32_e32 v61, v132, v130
	v_add_f32_e32 v56, v200, v56
	v_exp_f32_e32 v204, v61
	v_sub_f32_e32 v61, v133, v130
	v_add_f32_e32 v56, v201, v56
	v_exp_f32_e32 v205, v61
	v_sub_f32_e32 v61, v134, v130
	v_add_f32_e32 v56, v202, v56
	v_exp_f32_e32 v206, v61
	v_sub_f32_e32 v61, v135, v130
	v_add_f32_e32 v56, v203, v56
	v_exp_f32_e32 v207, v61
	v_sub_f32_e32 v61, v136, v130
	v_add_f32_e32 v56, v204, v56
	v_exp_f32_e32 v208, v61
	v_sub_f32_e32 v61, v137, v130
	v_add_f32_e32 v56, v205, v56
	v_exp_f32_e32 v209, v61
	v_sub_f32_e32 v61, v142, v130
	v_add_f32_e32 v56, v206, v56
	v_exp_f32_e32 v210, v61
	v_sub_f32_e32 v61, v143, v130
	v_add_f32_e32 v56, v207, v56
	v_exp_f32_e32 v211, v61
	v_sub_f32_e32 v61, v144, v130
	v_add_f32_e32 v56, v208, v56
	v_exp_f32_e32 v144, v61
	v_sub_f32_e32 v61, v145, v130
	v_add_f32_e32 v56, v209, v56
	v_exp_f32_e32 v145, v61
	v_sub_f32_e32 v61, v146, v130
	v_add_f32_e32 v56, v210, v56
	v_exp_f32_e32 v146, v61
	v_sub_f32_e32 v61, v147, v130
	v_add_f32_e32 v56, v211, v56
	v_exp_f32_e32 v147, v61
	v_sub_f32_e32 v61, v138, v130
	v_add_f32_e32 v56, v144, v56
	v_exp_f32_e32 v132, v61
	v_sub_f32_e32 v61, v139, v130
	v_add_f32_e32 v56, v145, v56
	v_exp_f32_e32 v133, v61
	v_sub_f32_e32 v61, v140, v130
	v_add_f32_e32 v56, v146, v56
	v_exp_f32_e32 v134, v61
	v_sub_f32_e32 v61, v141, v130
	v_add_f32_e32 v56, v147, v56
	v_exp_f32_e32 v135, v61
	v_sub_f32_e32 v48, v48, v130
	v_add_f32_e32 v56, v132, v56
	v_exp_f32_e32 v136, v48
	v_sub_f32_e32 v48, v49, v130
	v_add_f32_e32 v56, v133, v56
	v_exp_f32_e32 v137, v48
	v_sub_f32_e32 v48, v50, v130
	v_add_f32_e32 v56, v134, v56
	v_exp_f32_e32 v138, v48
	v_sub_f32_e32 v48, v51, v130
	v_add_f32_e32 v56, v135, v56
	v_exp_f32_e32 v139, v48
	v_add_f32_e32 v48, v136, v56
	v_add_f32_e32 v48, v137, v48
	v_add_f32_e32 v48, v138, v48
	v_add_f32_e32 v48, v139, v48
	ds_bpermute_b32 v49, v86, v48
	v_cvt_pk_bf16_f32 v176, v52, v53
	v_cvt_pk_bf16_f32 v177, v54, v55
	v_cvt_pk_bf16_f32 v178, v57, v58
	v_cvt_pk_bf16_f32 v179, v59, v60
	s_waitcnt lgkmcnt(0)
	v_add_f32_e32 v48, v48, v49
	ds_bpermute_b32 v49, v87, v48
	s_waitcnt lgkmcnt(0)
	v_add_f32_e32 v131, v48, v49
	v_add_u32_e32 v48, s38, v88
	ds_read_b64_tr_b16 v[140:141], v48 offset:0
	ds_read_b64_tr_b16 v[142:143], v48 offset:0x440
	ds_read_b64_tr_b16 v[148:149], v48 offset:32
	ds_read_b64_tr_b16 v[150:151], v48 offset:0x460
	ds_read_b64_tr_b16 v[152:153], v48 offset:64
	ds_read_b64_tr_b16 v[154:155], v48 offset:0x480
	ds_read_b64_tr_b16 v[156:157], v48 offset:0x60
	ds_read_b64_tr_b16 v[158:159], v48 offset:0x4a0
	ds_read_b64_tr_b16 v[160:161], v48 offset:0x80
	ds_read_b64_tr_b16 v[162:163], v48 offset:0x4c0
	ds_read_b64_tr_b16 v[164:165], v48 offset:0xa0
	ds_read_b64_tr_b16 v[166:167], v48 offset:0x4e0
	ds_read_b64_tr_b16 v[168:169], v48 offset:0xc0
	ds_read_b64_tr_b16 v[170:171], v48 offset:0x500
	ds_read_b64_tr_b16 v[172:173], v48 offset:0xe0
	ds_read_b64_tr_b16 v[174:175], v48 offset:0x520
	s_waitcnt lgkmcnt(0)
	v_add_u32_e32 v198, s33, v88
	ds_read_b64_tr_b16 v[184:185], v198 offset:0
	ds_read_b64_tr_b16 v[186:187], v198 offset:0x440
	ds_read_b64_tr_b16 v[188:189], v198 offset:32
	ds_read_b64_tr_b16 v[190:191], v198 offset:0x460
	ds_read_b64_tr_b16 v[68:69], v198 offset:64
	ds_read_b64_tr_b16 v[70:71], v198 offset:0x480
	ds_read_b64_tr_b16 v[64:65], v198 offset:0x60
	ds_read_b64_tr_b16 v[66:67], v198 offset:0x4a0
	ds_read_b64_tr_b16 v[60:61], v198 offset:0x80
	ds_read_b64_tr_b16 v[62:63], v198 offset:0x4c0
	ds_read_b64_tr_b16 v[56:57], v198 offset:0xa0
	ds_read_b64_tr_b16 v[58:59], v198 offset:0x4e0
	ds_read_b64_tr_b16 v[52:53], v198 offset:0xc0
	ds_read_b64_tr_b16 v[54:55], v198 offset:0x500
	ds_read_b64_tr_b16 v[48:49], v198 offset:0xe0
	ds_read_b64_tr_b16 v[50:51], v198 offset:0x520
	s_waitcnt lgkmcnt(0)
	v_mfma_f32_16x16x32_bf16 v[140:143], v[140:143], v[176:179], 0
	v_mfma_f32_16x16x32_bf16 v[148:151], v[148:151], v[176:179], 0
	v_mfma_f32_16x16x32_bf16 v[152:155], v[152:155], v[176:179], 0
	v_mfma_f32_16x16x32_bf16 v[156:159], v[156:159], v[176:179], 0
	v_mfma_f32_16x16x32_bf16 v[160:163], v[160:163], v[176:179], 0
	v_mfma_f32_16x16x32_bf16 v[164:167], v[164:167], v[176:179], 0
	v_mfma_f32_16x16x32_bf16 v[168:171], v[168:171], v[176:179], 0
	v_mfma_f32_16x16x32_bf16 v[172:175], v[172:175], v[176:179], 0
	v_cvt_pk_bf16_f32 v176, v181, v183
	v_cvt_pk_bf16_f32 v177, v192, v193
	v_cvt_pk_bf16_f32 v178, v194, v195
	v_cvt_pk_bf16_f32 v179, v196, v197
	s_nop 1
	v_mfma_f32_16x16x32_bf16 v[140:143], v[184:187], v[176:179], v[140:143]
	v_add_u32_e32 v181, s2, v88
	ds_read_b64_tr_b16 v[184:185], v181 offset:0
	ds_read_b64_tr_b16 v[186:187], v181 offset:0x440
	v_mfma_f32_16x16x32_bf16 v[148:151], v[188:191], v[176:179], v[148:151]
	ds_read_b64_tr_b16 v[188:189], v181 offset:32
	ds_read_b64_tr_b16 v[190:191], v181 offset:0x460
	ds_read_b64_tr_b16 v[192:193], v181 offset:64
	ds_read_b64_tr_b16 v[194:195], v181 offset:0x480
	v_mfma_f32_16x16x32_bf16 v[68:71], v[68:71], v[176:179], v[152:155]
	ds_read_b64_tr_b16 v[152:153], v181 offset:0x60
	ds_read_b64_tr_b16 v[154:155], v181 offset:0x4a0
	v_cvt_pk_bf16_f32 v200, v200, v201
	v_mfma_f32_16x16x32_bf16 v[64:67], v[64:67], v[176:179], v[156:159]
	ds_read_b64_tr_b16 v[156:157], v181 offset:0x80
	ds_read_b64_tr_b16 v[158:159], v181 offset:0x4c0
	ds_read_b64_tr_b16 v[196:197], v181 offset:0xa0
	ds_read_b64_tr_b16 v[198:199], v181 offset:0x4e0
	v_mfma_f32_16x16x32_bf16 v[60:63], v[60:63], v[176:179], v[160:163]
	ds_read_b64_tr_b16 v[160:161], v181 offset:0xc0
	ds_read_b64_tr_b16 v[162:163], v181 offset:0x500
	v_cvt_pk_bf16_f32 v201, v202, v203
	v_mfma_f32_16x16x32_bf16 v[56:59], v[56:59], v[176:179], v[164:167]
	ds_read_b64_tr_b16 v[164:165], v181 offset:0xe0
	ds_read_b64_tr_b16 v[166:167], v181 offset:0x520
	s_waitcnt lgkmcnt(0)
	v_mfma_f32_16x16x32_bf16 v[48:51], v[48:51], v[176:179], v[172:175]
	v_cvt_pk_bf16_f32 v202, v204, v205
	v_cvt_pk_bf16_f32 v203, v206, v207
	v_mfma_f32_16x16x32_bf16 v[52:55], v[52:55], v[176:179], v[168:171]
	v_add_u32_e32 v181, s41, v88
	ds_read_b64_tr_b16 v[168:169], v181 offset:0
	ds_read_b64_tr_b16 v[170:171], v181 offset:0x440
	ds_read_b64_tr_b16 v[172:173], v181 offset:32
	ds_read_b64_tr_b16 v[174:175], v181 offset:0x460
	ds_read_b64_tr_b16 v[176:177], v181 offset:64
	ds_read_b64_tr_b16 v[178:179], v181 offset:0x480
	v_mfma_f32_16x16x32_bf16 v[140:143], v[184:187], v[200:203], v[140:143]
	ds_read_b64_tr_b16 v[184:185], v181 offset:0x60
	ds_read_b64_tr_b16 v[186:187], v181 offset:0x4a0
	v_mfma_f32_16x16x32_bf16 v[64:67], v[152:155], v[200:203], v[64:67]
	ds_read_b64_tr_b16 v[152:153], v181 offset:0x80
	ds_read_b64_tr_b16 v[154:155], v181 offset:0x4c0
	v_mfma_f32_16x16x32_bf16 v[148:151], v[188:191], v[200:203], v[148:151]
	ds_read_b64_tr_b16 v[188:189], v181 offset:0xa0
	ds_read_b64_tr_b16 v[190:191], v181 offset:0x4e0
	v_mfma_f32_16x16x32_bf16 v[60:63], v[156:159], v[200:203], v[60:63]
	ds_read_b64_tr_b16 v[156:157], v181 offset:0xc0
	ds_read_b64_tr_b16 v[158:159], v181 offset:0x500
	v_mfma_f32_16x16x32_bf16 v[68:71], v[192:195], v[200:203], v[68:71]
	ds_read_b64_tr_b16 v[192:193], v181 offset:0xe0
	ds_read_b64_tr_b16 v[194:195], v181 offset:0x520
	s_waitcnt lgkmcnt(0)
	v_mfma_f32_16x16x32_bf16 v[48:51], v[164:167], v[200:203], v[48:51]
	v_mfma_f32_16x16x32_bf16 v[56:59], v[196:199], v[200:203], v[56:59]
	v_cvt_pk_bf16_f32 v196, v208, v209
	v_cvt_pk_bf16_f32 v197, v210, v211
	v_cvt_pk_bf16_f32 v198, v144, v145
	v_mfma_f32_16x16x32_bf16 v[52:55], v[160:163], v[200:203], v[52:55]
	v_cvt_pk_bf16_f32 v199, v146, v147
	v_add_u32_e32 v144, s40, v88
	ds_read_b64_tr_b16 v[160:161], v144 offset:0
	ds_read_b64_tr_b16 v[162:163], v144 offset:0x440
	ds_read_b64_tr_b16 v[164:165], v144 offset:32
	ds_read_b64_tr_b16 v[166:167], v144 offset:0x460
	s_nop 0
	v_mfma_f32_16x16x32_bf16 v[140:143], v[168:171], v[196:199], v[140:143]
	ds_read_b64_tr_b16 v[168:169], v144 offset:64
	ds_read_b64_tr_b16 v[170:171], v144 offset:0x480
	v_mfma_f32_16x16x32_bf16 v[148:151], v[172:175], v[196:199], v[148:151]
	ds_read_b64_tr_b16 v[172:173], v144 offset:0x60
	ds_read_b64_tr_b16 v[174:175], v144 offset:0x4a0
	v_mfma_f32_16x16x32_bf16 v[60:63], v[152:155], v[196:199], v[60:63]
	ds_read_b64_tr_b16 v[152:153], v144 offset:0x80
	ds_read_b64_tr_b16 v[154:155], v144 offset:0x4c0
	v_mfma_f32_16x16x32_bf16 v[68:71], v[176:179], v[196:199], v[68:71]
	ds_read_b64_tr_b16 v[176:177], v144 offset:0xa0
	ds_read_b64_tr_b16 v[178:179], v144 offset:0x4e0
	v_mfma_f32_16x16x32_bf16 v[64:67], v[184:187], v[196:199], v[64:67]
	ds_read_b64_tr_b16 v[184:185], v144 offset:0xc0
	ds_read_b64_tr_b16 v[186:187], v144 offset:0x500
	v_mfma_f32_16x16x32_bf16 v[52:55], v[156:159], v[196:199], v[52:55]
	ds_read_b64_tr_b16 v[156:157], v144 offset:0xe0
	ds_read_b64_tr_b16 v[158:159], v144 offset:0x520
	s_waitcnt lgkmcnt(0)
	v_mfma_f32_16x16x32_bf16 v[56:59], v[188:191], v[196:199], v[56:59]
	v_mfma_f32_16x16x32_bf16 v[188:191], v[192:195], v[196:199], v[48:51]
	v_cvt_pk_bf16_f32 v132, v132, v133
	v_cvt_pk_bf16_f32 v133, v134, v135
	v_cvt_pk_bf16_f32 v134, v136, v137
	v_cvt_pk_bf16_f32 v135, v138, v139
	v_rcp_f32_e32 v144, v131
	v_add_u32_e32 v48, s95, v129
	v_mfma_f32_16x16x32_bf16 v[136:139], v[160:163], v[132:135], v[140:143]
	v_ashrrev_i32_e32 v49, 31, v48
	v_lshl_add_u64 v[48:49], s[64:65], 0, v[48:49]
	v_lshlrev_b64 v[50:51], 11, v[48:49]
	v_mfma_f32_16x16x32_bf16 v[140:143], v[164:167], v[132:135], v[148:151]
	v_lshl_add_u64 v[146:147], v[78:79], 0, v[50:51]
	s_nop 2
	v_pk_mul_f32 v[50:51], v[144:145], v[136:137] op_sel_hi:[0,1]
	v_pk_mul_f32 v[136:137], v[144:145], v[138:139] op_sel_hi:[0,1]
	v_mfma_f32_16x16x32_bf16 v[68:71], v[168:171], v[132:135], v[68:71]
	v_cvt_pk_bf16_f32 v50, v50, v51
	v_cvt_pk_bf16_f32 v51, v136, v137
	global_store_dwordx2 v[146:147], v[50:51], off nt
	v_mfma_f32_16x16x32_bf16 v[64:67], v[172:175], v[132:135], v[64:67]
	v_mul_f32_e64 v50, v144, v140
	v_mul_f32_e64 v51, v144, v141
	v_pk_mul_f32 v[136:137], v[144:145], v[142:143] op_sel_hi:[0,1]
	v_cvt_pk_bf16_f32 v50, v50, v51
	v_cvt_pk_bf16_f32 v51, v136, v137
	v_mfma_f32_16x16x32_bf16 v[60:63], v[152:155], v[132:135], v[60:63]
	global_store_dwordx2 v[146:147], v[50:51], off offset:32 nt
	v_pk_mul_f32 v[136:137], v[144:145], v[70:71] op_sel_hi:[0,1]
	v_mfma_f32_16x16x32_bf16 v[50:53], v[184:187], v[132:135], v[52:55]
	s_nop 2
	v_mul_f32_e64 v54, v144, v68
	v_mul_f32_e64 v55, v144, v69
	v_cvt_pk_bf16_f32 v54, v54, v55
	v_cvt_pk_bf16_f32 v55, v136, v137
	v_mfma_f32_16x16x32_bf16 v[56:59], v[176:179], v[132:135], v[56:59]
	global_store_dwordx2 v[146:147], v[54:55], off offset:64 nt
	v_pk_mul_f32 v[54:55], v[144:145], v[64:65] op_sel_hi:[0,1]
	v_pk_mul_f32 v[64:65], v[144:145], v[66:67] op_sel_hi:[0,1]
	v_mfma_f32_16x16x32_bf16 v[68:71], v[156:159], v[132:135], v[188:191]
	v_cvt_pk_bf16_f32 v54, v54, v55
	v_cvt_pk_bf16_f32 v55, v64, v65
	global_store_dwordx2 v[146:147], v[54:55], off offset:96 nt
	v_pk_mul_f32 v[54:55], v[144:145], v[60:61] op_sel_hi:[0,1]
	v_pk_mul_f32 v[60:61], v[144:145], v[62:63] op_sel_hi:[0,1]
	v_pk_mul_f32 v[50:51], v[144:145], v[50:51] op_sel_hi:[0,1]
	v_pk_mul_f32 v[52:53], v[144:145], v[52:53] op_sel_hi:[0,1]
	v_cvt_pk_bf16_f32 v54, v54, v55
	v_cvt_pk_bf16_f32 v55, v60, v61
	v_cvt_pk_bf16_f32 v50, v50, v51
	v_cvt_pk_bf16_f32 v51, v52, v53
	global_store_dwordx2 v[146:147], v[54:55], off offset:128 nt
	v_pk_mul_f32 v[54:55], v[144:145], v[56:57] op_sel_hi:[0,1]
	v_pk_mul_f32 v[56:57], v[144:145], v[58:59] op_sel_hi:[0,1]
	global_store_dwordx2 v[146:147], v[50:51], off offset:192 nt
	v_pk_mul_f32 v[50:51], v[144:145], v[68:69] op_sel_hi:[0,1]
	v_pk_mul_f32 v[52:53], v[144:145], v[70:71] op_sel_hi:[0,1]
	v_cvt_pk_bf16_f32 v54, v54, v55
	v_cvt_pk_bf16_f32 v55, v56, v57
	v_cvt_pk_bf16_f32 v50, v50, v51
	v_cvt_pk_bf16_f32 v51, v52, v53
	global_store_dwordx2 v[146:147], v[54:55], off offset:160 nt
	global_store_dwordx2 v[146:147], v[50:51], off offset:224 nt
	s_and_saveexec_b64 s[40:41], s[0:1]
	s_cbranch_execz .LBB0_256
	v_log_f32_e32 v50, v131
	v_lshlrev_b64 v[48:49], 5, v[48:49]
	v_lshl_add_u64 v[48:49], s[88:89], 0, v[48:49]
	v_add_f32_e32 v50, v130, v50
	v_mul_f32_e32 v50, 0x3f317218, v50
	global_store_dword v[48:49], v50, off

.LBB0_414:
	s_add_i32 s40, s53, -1
	s_add_i32 s42, s52, s3
	s_and_b32 s94, s40, 1
	s_and_b32 s43, s53, 1
	s_and_b64 s[40:41], s[64:65], exec
	s_cselect_b32 s40, s94, s43
	s_mul_i32 s63, s40, 0x11000
	s_add_i32 s63, s63, s97
	s_and_b64 s[40:41], s[66:67], exec
	s_cselect_b32 s40, s94, s43
	s_mul_i32 s62, s40, 0x11000
	s_add_i32 s62, s62, s0
	s_and_b64 s[40:41], s[68:69], exec
	v_add_u32_e32 v150, s63, v84
	v_add_u32_e32 v178, s62, v84
	v_lshlrev_b32_e32 v129, s48, v64
	s_cselect_b32 s40, s94, s43
	ds_read_b128 v[64:67], v150
	ds_read_b128 v[68:71], v150 offset:64
	ds_read_b128 v[130:133], v150 offset:128
	ds_read_b128 v[134:137], v150 offset:192
	ds_read_b128 v[138:141], v150 offset:1088
	ds_read_b128 v[142:145], v150 offset:1152
	ds_read_b128 v[146:149], v150 offset:1216
	ds_read_b128 v[150:153], v150 offset:1280
	ds_read_b128 v[154:157], v178
	ds_read_b128 v[158:161], v178 offset:64
	ds_read_b128 v[162:165], v178 offset:128
	ds_read_b128 v[166:169], v178 offset:192
	ds_read_b128 v[170:173], v178 offset:1088
	ds_read_b128 v[174:177], v178 offset:1152
	ds_read_b128 v[184:187], v178 offset:1216
	ds_read_b128 v[188:191], v178 offset:1280
	s_mul_i32 s95, s40, 0x11000
	s_add_i32 s95, s95, s1
	s_and_b64 s[40:41], s[70:71], exec
	s_cselect_b32 s40, s94, s43
	s_mul_i32 s41, s40, 0x11000
	s_add_i32 s41, s41, s93
	s_and_b64 s[60:61], s[72:73], exec
	s_cselect_b32 s40, s94, s43
	s_mul_i32 s40, s40, 0x11000
	s_add_i32 s40, s40, s97
	s_waitcnt lgkmcnt(14)
	v_mfma_f32_16x16x32_bf16 v[64:67], v[64:67], v[48:51], 0
	v_mfma_f32_16x16x32_bf16 v[64:67], v[68:71], v[52:55], v[64:67]
	s_waitcnt lgkmcnt(11)
	v_mfma_f32_16x16x32_bf16 v[68:71], v[138:141], v[48:51], 0
	s_waitcnt lgkmcnt(10)
	v_mfma_f32_16x16x32_bf16 v[68:71], v[142:145], v[52:55], v[68:71]
	v_mfma_f32_16x16x32_bf16 v[64:67], v[130:133], v[56:59], v[64:67]
	s_waitcnt lgkmcnt(9)
	v_mfma_f32_16x16x32_bf16 v[68:71], v[146:149], v[56:59], v[68:71]
	v_mfma_f32_16x16x32_bf16 v[64:67], v[134:137], v[60:63], v[64:67]
	s_waitcnt lgkmcnt(8)
	v_mfma_f32_16x16x32_bf16 v[68:71], v[150:153], v[60:63], v[68:71]
	v_add_u32_e32 v178, s95, v84
	ds_read_b128 v[130:133], v178
	ds_read_b128 v[134:137], v178 offset:64
	ds_read_b128 v[138:141], v178 offset:128
	ds_read_b128 v[142:145], v178 offset:192
	ds_read_b128 v[146:149], v178 offset:1088
	ds_read_b128 v[150:153], v178 offset:1152
	ds_read_b128 v[192:195], v178 offset:1216
	ds_read_b128 v[196:199], v178 offset:1280
	s_waitcnt lgkmcnt(14)
	v_mfma_f32_16x16x32_bf16 v[154:157], v[154:157], v[48:51], 0
	v_mfma_f32_16x16x32_bf16 v[154:157], v[158:161], v[52:55], v[154:157]
	s_waitcnt lgkmcnt(11)
	v_mfma_f32_16x16x32_bf16 v[158:161], v[170:173], v[48:51], 0
	s_waitcnt lgkmcnt(10)
	v_mfma_f32_16x16x32_bf16 v[158:161], v[174:177], v[52:55], v[158:161]
	v_mfma_f32_16x16x32_bf16 v[154:157], v[162:165], v[56:59], v[154:157]
	s_waitcnt lgkmcnt(9)
	v_mfma_f32_16x16x32_bf16 v[158:161], v[184:187], v[56:59], v[158:161]
	v_mfma_f32_16x16x32_bf16 v[154:157], v[166:169], v[60:63], v[154:157]
	s_waitcnt lgkmcnt(8)
	v_mfma_f32_16x16x32_bf16 v[158:161], v[188:191], v[60:63], v[158:161]
	v_add_u32_e32 v178, s41, v84
	ds_read_b128 v[162:165], v178
	ds_read_b128 v[166:169], v178 offset:64
	ds_read_b128 v[170:173], v178 offset:128
	ds_read_b128 v[174:177], v178 offset:192
	ds_read_b128 v[184:187], v178 offset:1088
	ds_read_b128 v[188:191], v178 offset:1152
	ds_read_b128 v[200:203], v178 offset:1216
	ds_read_b128 v[204:207], v178 offset:1280
	s_waitcnt lgkmcnt(14)
	v_mfma_f32_16x16x32_bf16 v[130:133], v[130:133], v[48:51], 0
	v_mfma_f32_16x16x32_bf16 v[130:133], v[134:137], v[52:55], v[130:133]
	s_waitcnt lgkmcnt(11)
	v_mfma_f32_16x16x32_bf16 v[134:137], v[146:149], v[48:51], 0
	v_mfma_f32_16x16x32_bf16 v[130:133], v[138:141], v[56:59], v[130:133]
	s_waitcnt lgkmcnt(10)
	v_mfma_f32_16x16x32_bf16 v[134:137], v[150:153], v[52:55], v[134:137]
	v_mfma_f32_16x16x32_bf16 v[130:133], v[142:145], v[60:63], v[130:133]
	s_waitcnt lgkmcnt(9)
	v_mfma_f32_16x16x32_bf16 v[134:137], v[192:195], v[56:59], v[134:137]
	s_waitcnt lgkmcnt(8)
	v_mfma_f32_16x16x32_bf16 v[134:137], v[196:199], v[60:63], v[134:137]
	v_add_u32_e32 v178, s40, v84
	ds_read_b128 v[138:141], v178
	ds_read_b128 v[142:145], v178 offset:64
	ds_read_b128 v[146:149], v178 offset:128
	ds_read_b128 v[150:153], v178 offset:192
	ds_read_b128 v[192:195], v178 offset:1088
	ds_read_b128 v[196:199], v178 offset:1152
	ds_read_b128 v[208:211], v178 offset:1216
	ds_read_b128 v[212:215], v178 offset:1280
	s_waitcnt lgkmcnt(14)
	v_mfma_f32_16x16x32_bf16 v[162:165], v[162:165], v[48:51], 0
	v_mfma_f32_16x16x32_bf16 v[162:165], v[166:169], v[52:55], v[162:165]
	s_waitcnt lgkmcnt(11)
	v_mfma_f32_16x16x32_bf16 v[166:169], v[184:187], v[48:51], 0
	s_waitcnt lgkmcnt(10)
	v_mfma_f32_16x16x32_bf16 v[166:169], v[188:191], v[52:55], v[166:169]
	v_mfma_f32_16x16x32_bf16 v[162:165], v[170:173], v[56:59], v[162:165]
	s_waitcnt lgkmcnt(9)
	v_mfma_f32_16x16x32_bf16 v[166:169], v[200:203], v[56:59], v[166:169]
	v_mfma_f32_16x16x32_bf16 v[162:165], v[174:177], v[60:63], v[162:165]
	s_waitcnt lgkmcnt(8)
	v_mfma_f32_16x16x32_bf16 v[166:169], v[204:207], v[60:63], v[166:169]
	s_waitcnt lgkmcnt(7)
	v_mfma_f32_16x16x32_bf16 v[138:141], v[138:141], v[48:51], 0
	s_waitcnt lgkmcnt(3)
	v_mfma_f32_16x16x32_bf16 v[48:51], v[192:195], v[48:51], 0
	s_waitcnt lgkmcnt(2)
	v_mfma_f32_16x16x32_bf16 v[48:51], v[196:199], v[52:55], v[48:51]
	v_mfma_f32_16x16x32_bf16 v[138:141], v[142:145], v[52:55], v[138:141]
	s_waitcnt lgkmcnt(1)
	v_mfma_f32_16x16x32_bf16 v[48:51], v[208:211], v[56:59], v[48:51]
	v_mfma_f32_16x16x32_bf16 v[138:141], v[146:149], v[56:59], v[138:141]
	s_waitcnt lgkmcnt(0)
	v_mfma_f32_16x16x32_bf16 v[48:51], v[212:215], v[60:63], v[48:51]
	v_mfma_f32_16x16x32_bf16 v[138:141], v[150:153], v[60:63], v[138:141]
	s_cmp_lg_u32 s42, 0
	s_cselect_b64 s[60:61], -1, 0
	s_or_b64 s[42:43], s[60:61], s[74:75]
	v_fmamk_f32 v52, v64, 0x3e0293ee, v89
	s_and_b64 vcc, s[42:43], s[6:7]
	v_cndmask_b32_e32 v52, v82, v52, vcc
	v_fmamk_f32 v53, v65, 0x3e0293ee, v90
	s_and_b64 vcc, s[42:43], s[8:9]
	v_cndmask_b32_e32 v53, v82, v53, vcc
	v_fmamk_f32 v55, v66, 0x3e0293ee, v91
	s_and_b64 vcc, s[42:43], s[10:11]
	v_cndmask_b32_e32 v55, v82, v55, vcc
	v_fmamk_f32 v56, v67, 0x3e0293ee, v92
	s_and_b64 vcc, s[42:43], s[12:13]
	v_cndmask_b32_e32 v56, v82, v56, vcc
	v_fmamk_f32 v57, v68, 0x3e0293ee, v93
	s_and_b64 vcc, s[42:43], s[14:15]
	v_cndmask_b32_e32 v57, v82, v57, vcc
	v_fmamk_f32 v58, v69, 0x3e0293ee, v94
	s_and_b64 vcc, s[42:43], s[16:17]
	v_cndmask_b32_e32 v58, v82, v58, vcc
	v_fmamk_f32 v59, v70, 0x3e0293ee, v95
	s_and_b64 vcc, s[42:43], s[18:19]
	v_cndmask_b32_e32 v59, v82, v59, vcc
	v_fmamk_f32 v60, v71, 0x3e0293ee, v96
	s_and_b64 vcc, s[42:43], s[20:21]
	v_cndmask_b32_e32 v60, v82, v60, vcc
	v_fmamk_f32 v61, v154, 0x3e0293ee, v97
	s_or_b64 vcc, s[60:61], s[76:77]
	v_fmamk_f32 v62, v155, 0x3e0293ee, v98
	v_fmamk_f32 v63, v156, 0x3e0293ee, v99
	v_fmamk_f32 v64, v157, 0x3e0293ee, v100
	v_fmamk_f32 v65, v158, 0x3e0293ee, v101
	v_fmamk_f32 v66, v159, 0x3e0293ee, v102
	v_fmamk_f32 v67, v160, 0x3e0293ee, v103
	v_fmamk_f32 v68, v161, 0x3e0293ee, v104
	v_cndmask_b32_e32 v61, v82, v61, vcc
	v_cndmask_b32_e32 v62, v82, v62, vcc
	v_cndmask_b32_e32 v63, v82, v63, vcc
	v_cndmask_b32_e32 v64, v82, v64, vcc
	v_cndmask_b32_e32 v65, v82, v65, vcc
	v_cndmask_b32_e32 v66, v82, v66, vcc
	v_cndmask_b32_e32 v67, v82, v67, vcc
	v_cndmask_b32_e32 v68, v82, v68, vcc
	v_fmamk_f32 v69, v130, 0x3e0293ee, v105
	s_or_b64 vcc, s[60:61], s[78:79]
	v_fmamk_f32 v130, v133, 0x3e0293ee, v108
	v_fmamk_f32 v70, v131, 0x3e0293ee, v106
	v_cndmask_b32_e32 v131, v82, v130, vcc
	v_fmamk_f32 v130, v134, 0x3e0293ee, v109
	s_mov_b32 s33, 0xff800000
	v_fmamk_f32 v71, v132, 0x3e0293ee, v107
	v_cndmask_b32_e32 v132, v82, v130, vcc
	v_fmamk_f32 v130, v135, 0x3e0293ee, v110
	v_max3_f32 v54, v52, s33, v53
	v_cndmask_b32_e32 v133, v82, v130, vcc
	v_fmamk_f32 v130, v136, 0x3e0293ee, v111
	v_max3_f32 v54, v54, v55, v56
	v_cndmask_b32_e32 v134, v82, v130, vcc
	v_fmamk_f32 v130, v137, 0x3e0293ee, v112
	v_max3_f32 v54, v54, v57, v58
	v_cndmask_b32_e32 v69, v82, v69, vcc
	v_cndmask_b32_e32 v70, v82, v70, vcc
	v_cndmask_b32_e32 v71, v82, v71, vcc
	v_cndmask_b32_e32 v135, v82, v130, vcc
	v_fmamk_f32 v130, v162, 0x3e0293ee, v113
	s_or_b64 vcc, s[60:61], s[80:81]
	v_max3_f32 v54, v54, v59, v60
	v_cndmask_b32_e32 v136, v82, v130, vcc
	v_fmamk_f32 v130, v163, 0x3e0293ee, v114
	v_max3_f32 v54, v54, v61, v62
	v_cndmask_b32_e32 v137, v82, v130, vcc
	v_fmamk_f32 v130, v164, 0x3e0293ee, v115
	v_max3_f32 v54, v54, v63, v64
	v_cndmask_b32_e32 v142, v82, v130, vcc
	v_fmamk_f32 v130, v165, 0x3e0293ee, v116
	v_max3_f32 v54, v54, v65, v66
	v_cndmask_b32_e32 v143, v82, v130, vcc
	v_fmamk_f32 v130, v166, 0x3e0293ee, v117
	v_max3_f32 v54, v54, v67, v68
	v_cndmask_b32_e32 v144, v82, v130, vcc
	v_fmamk_f32 v130, v167, 0x3e0293ee, v118
	v_max3_f32 v54, v54, v69, v70
	v_cndmask_b32_e32 v145, v82, v130, vcc
	v_fmamk_f32 v130, v168, 0x3e0293ee, v119
	v_max3_f32 v54, v54, v71, v131
	v_cndmask_b32_e32 v146, v82, v130, vcc
	v_fmamk_f32 v130, v169, 0x3e0293ee, v120
	s_or_b64 s[42:43], s[60:61], s[82:83]
	v_max3_f32 v54, v54, v132, v133
	v_cndmask_b32_e32 v147, v82, v130, vcc
	v_fmamk_f32 v130, v138, 0x3e0293ee, v121
	s_and_b64 vcc, s[42:43], s[22:23]
	v_max3_f32 v54, v54, v134, v135
	v_cndmask_b32_e32 v138, v82, v130, vcc
	v_fmamk_f32 v130, v139, 0x3e0293ee, v122
	s_and_b64 vcc, s[42:43], s[24:25]
	v_max3_f32 v54, v54, v136, v137
	v_cndmask_b32_e32 v139, v82, v130, vcc
	v_fmamk_f32 v130, v140, 0x3e0293ee, v123
	s_and_b64 vcc, s[42:43], s[26:27]
	v_max3_f32 v54, v54, v142, v143
	v_cndmask_b32_e32 v140, v82, v130, vcc
	v_fmamk_f32 v130, v141, 0x3e0293ee, v124
	s_and_b64 vcc, s[42:43], s[28:29]
	v_max3_f32 v54, v54, v144, v145
	v_cndmask_b32_e32 v141, v82, v130, vcc
	v_fmamk_f32 v48, v48, 0x3e0293ee, v125
	s_and_b64 vcc, s[42:43], s[30:31]
	v_max3_f32 v54, v54, v146, v147
	v_cndmask_b32_e32 v48, v82, v48, vcc
	v_fmamk_f32 v49, v49, 0x3e0293ee, v126
	s_and_b64 vcc, s[42:43], s[34:35]
	v_max3_f32 v54, v54, v138, v139
	v_cndmask_b32_e32 v49, v82, v49, vcc
	v_fmamk_f32 v50, v50, 0x3e0293ee, v127
	s_and_b64 vcc, s[42:43], s[36:37]
	v_max3_f32 v54, v54, v140, v141
	v_cndmask_b32_e32 v50, v82, v50, vcc
	v_fmamk_f32 v51, v51, 0x3e0293ee, v85
	s_and_b64 vcc, s[42:43], s[38:39]
	v_max3_f32 v54, v54, v48, v49
	v_cndmask_b32_e32 v51, v82, v51, vcc
	v_max3_f32 v54, v54, v50, v51
	ds_bpermute_b32 v130, v86, v54
	s_waitcnt lgkmcnt(0)
	v_max_f32_e32 v130, v130, v130
	v_max_f32_e32 v54, v54, v130
	ds_bpermute_b32 v130, v87, v54
	s_waitcnt lgkmcnt(0)
	v_max_f32_e32 v130, v130, v130
	v_max_f32_e32 v130, v54, v130
	v_sub_f32_e32 v52, v52, v130
	v_exp_f32_e32 v52, v52
	v_sub_f32_e32 v53, v53, v130
	v_exp_f32_e32 v53, v53
	v_sub_f32_e32 v54, v55, v130
	v_exp_f32_e32 v54, v54
	v_sub_f32_e32 v55, v56, v130
	v_exp_f32_e32 v55, v55
	v_sub_f32_e32 v57, v57, v130
	v_add_f32_e32 v56, 0, v52
	v_exp_f32_e32 v57, v57
	v_sub_f32_e32 v58, v58, v130
	v_add_f32_e32 v56, v53, v56
	v_exp_f32_e32 v58, v58
	v_sub_f32_e32 v59, v59, v130
	v_add_f32_e32 v56, v54, v56
	v_exp_f32_e32 v59, v59
	v_sub_f32_e32 v60, v60, v130
	v_add_f32_e32 v56, v55, v56
	v_exp_f32_e32 v60, v60
	v_sub_f32_e32 v61, v61, v130
	v_add_f32_e32 v56, v57, v56
	v_exp_f32_e32 v181, v61
	v_sub_f32_e32 v61, v62, v130
	v_add_f32_e32 v56, v58, v56
	v_exp_f32_e32 v183, v61
	v_sub_f32_e32 v61, v63, v130
	v_add_f32_e32 v56, v59, v56
	v_exp_f32_e32 v188, v61
	v_sub_f32_e32 v61, v64, v130
	v_add_f32_e32 v56, v60, v56
	v_exp_f32_e32 v189, v61
	v_sub_f32_e32 v61, v65, v130
	v_add_f32_e32 v56, v181, v56
	v_exp_f32_e32 v190, v61
	v_sub_f32_e32 v61, v66, v130
	v_add_f32_e32 v56, v183, v56
	v_exp_f32_e32 v191, v61
	v_sub_f32_e32 v61, v67, v130
	v_add_f32_e32 v56, v188, v56
	v_exp_f32_e32 v192, v61
	v_sub_f32_e32 v61, v68, v130
	v_add_f32_e32 v56, v189, v56
	v_exp_f32_e32 v193, v61
	v_sub_f32_e32 v61, v69, v130
	v_add_f32_e32 v56, v190, v56
	v_exp_f32_e32 v196, v61
	v_sub_f32_e32 v61, v70, v130
	v_add_f32_e32 v56, v191, v56
	v_exp_f32_e32 v197, v61
	v_sub_f32_e32 v61, v71, v130
	v_add_f32_e32 v56, v192, v56
	v_exp_f32_e32 v198, v61
	v_sub_f32_e32 v61, v131, v130
	v_add_f32_e32 v56, v193, v56
	v_exp_f32_e32 v199, v61
	v_sub_f32_e32 v61, v132, v130
	v_add_f32_e32 v56, v196, v56
	v_exp_f32_e32 v200, v61
	v_sub_f32_e32 v61, v133, v130
	v_add_f32_e32 v56, v197, v56
	v_exp_f32_e32 v201, v61
	v_sub_f32_e32 v61, v134, v130
	v_add_f32_e32 v56, v198, v56
	v_exp_f32_e32 v202, v61
	v_sub_f32_e32 v61, v135, v130
	v_add_f32_e32 v56, v199, v56
	v_exp_f32_e32 v203, v61
	v_sub_f32_e32 v61, v136, v130
	v_add_f32_e32 v56, v200, v56
	v_exp_f32_e32 v204, v61
	v_sub_f32_e32 v61, v137, v130
	v_add_f32_e32 v56, v201, v56
	v_exp_f32_e32 v205, v61
	v_sub_f32_e32 v61, v142, v130
	v_add_f32_e32 v56, v202, v56
	v_exp_f32_e32 v206, v61
	v_sub_f32_e32 v61, v143, v130
	v_add_f32_e32 v56, v203, v56
	v_exp_f32_e32 v207, v61
	v_sub_f32_e32 v61, v144, v130
	v_add_f32_e32 v56, v204, v56
	v_exp_f32_e32 v208, v61
	v_sub_f32_e32 v61, v145, v130
	v_add_f32_e32 v56, v205, v56
	v_exp_f32_e32 v209, v61
	v_sub_f32_e32 v61, v146, v130
	v_add_f32_e32 v56, v206, v56
	v_exp_f32_e32 v210, v61
	v_sub_f32_e32 v61, v147, v130
	v_add_f32_e32 v56, v207, v56
	v_exp_f32_e32 v211, v61
	v_sub_f32_e32 v61, v138, v130
	v_add_f32_e32 v56, v208, v56
	v_exp_f32_e32 v132, v61
	v_sub_f32_e32 v61, v139, v130
	v_add_f32_e32 v56, v209, v56
	v_exp_f32_e32 v133, v61
	v_sub_f32_e32 v61, v140, v130
	v_add_f32_e32 v56, v210, v56
	v_exp_f32_e32 v134, v61
	v_sub_f32_e32 v61, v141, v130
	v_add_f32_e32 v56, v211, v56
	v_exp_f32_e32 v135, v61
	v_sub_f32_e32 v48, v48, v130
	v_add_f32_e32 v56, v132, v56
	v_exp_f32_e32 v136, v48
	v_sub_f32_e32 v48, v49, v130
	v_add_f32_e32 v56, v133, v56
	v_exp_f32_e32 v137, v48
	v_sub_f32_e32 v48, v50, v130
	v_add_f32_e32 v56, v134, v56
	v_exp_f32_e32 v138, v48
	v_sub_f32_e32 v48, v51, v130
	v_add_f32_e32 v56, v135, v56
	v_exp_f32_e32 v139, v48
	v_add_f32_e32 v48, v136, v56
	v_add_f32_e32 v48, v137, v48
	v_add_f32_e32 v48, v138, v48
	v_add_f32_e32 v48, v139, v48
	ds_bpermute_b32 v49, v86, v48
	v_cvt_pk_bf16_f32 v172, v52, v53
	v_cvt_pk_bf16_f32 v173, v54, v55
	v_cvt_pk_bf16_f32 v174, v57, v58
	v_cvt_pk_bf16_f32 v175, v59, v60
	s_waitcnt lgkmcnt(0)
	v_add_f32_e32 v48, v48, v49
	ds_bpermute_b32 v49, v87, v48
	s_waitcnt lgkmcnt(0)
	v_add_f32_e32 v131, v48, v49
	v_add_u32_e32 v48, s63, v88
	ds_read_b64_tr_b16 v[140:141], v48 offset:0
	ds_read_b64_tr_b16 v[142:143], v48 offset:0x440
	ds_read_b64_tr_b16 v[144:145], v48 offset:32
	ds_read_b64_tr_b16 v[146:147], v48 offset:0x460
	ds_read_b64_tr_b16 v[148:149], v48 offset:64
	ds_read_b64_tr_b16 v[150:151], v48 offset:0x480
	ds_read_b64_tr_b16 v[152:153], v48 offset:0x60
	ds_read_b64_tr_b16 v[154:155], v48 offset:0x4a0
	ds_read_b64_tr_b16 v[156:157], v48 offset:0x80
	ds_read_b64_tr_b16 v[158:159], v48 offset:0x4c0
	ds_read_b64_tr_b16 v[160:161], v48 offset:0xa0
	ds_read_b64_tr_b16 v[162:163], v48 offset:0x4e0
	ds_read_b64_tr_b16 v[164:165], v48 offset:0xc0
	ds_read_b64_tr_b16 v[166:167], v48 offset:0x500
	ds_read_b64_tr_b16 v[168:169], v48 offset:0xe0
	ds_read_b64_tr_b16 v[170:171], v48 offset:0x520
	s_waitcnt lgkmcnt(0)
	v_add_u32_e32 v194, s62, v88
	ds_read_b64_tr_b16 v[176:177], v194 offset:0
	ds_read_b64_tr_b16 v[178:179], v194 offset:0x440
	ds_read_b64_tr_b16 v[184:185], v194 offset:32
	ds_read_b64_tr_b16 v[186:187], v194 offset:0x460
	ds_read_b64_tr_b16 v[68:69], v194 offset:64
	ds_read_b64_tr_b16 v[70:71], v194 offset:0x480
	ds_read_b64_tr_b16 v[64:65], v194 offset:0x60
	ds_read_b64_tr_b16 v[66:67], v194 offset:0x4a0
	ds_read_b64_tr_b16 v[60:61], v194 offset:0x80
	ds_read_b64_tr_b16 v[62:63], v194 offset:0x4c0
	ds_read_b64_tr_b16 v[56:57], v194 offset:0xa0
	ds_read_b64_tr_b16 v[58:59], v194 offset:0x4e0
	ds_read_b64_tr_b16 v[52:53], v194 offset:0xc0
	ds_read_b64_tr_b16 v[54:55], v194 offset:0x500
	ds_read_b64_tr_b16 v[48:49], v194 offset:0xe0
	ds_read_b64_tr_b16 v[50:51], v194 offset:0x520
	s_waitcnt lgkmcnt(0)
	v_mfma_f32_16x16x32_bf16 v[140:143], v[140:143], v[172:175], 0
	v_mfma_f32_16x16x32_bf16 v[144:147], v[144:147], v[172:175], 0
	v_mfma_f32_16x16x32_bf16 v[148:151], v[148:151], v[172:175], 0
	v_mfma_f32_16x16x32_bf16 v[152:155], v[152:155], v[172:175], 0
	v_mfma_f32_16x16x32_bf16 v[156:159], v[156:159], v[172:175], 0
	v_mfma_f32_16x16x32_bf16 v[160:163], v[160:163], v[172:175], 0
	v_mfma_f32_16x16x32_bf16 v[164:167], v[164:167], v[172:175], 0
	v_mfma_f32_16x16x32_bf16 v[168:171], v[168:171], v[172:175], 0
	v_cvt_pk_bf16_f32 v172, v181, v183
	v_cvt_pk_bf16_f32 v173, v188, v189
	v_cvt_pk_bf16_f32 v174, v190, v191
	v_cvt_pk_bf16_f32 v175, v192, v193
	s_nop 1
	v_mfma_f32_16x16x32_bf16 v[140:143], v[176:179], v[172:175], v[140:143]
	v_add_u32_e32 v181, s95, v88
	ds_read_b64_tr_b16 v[176:177], v181 offset:0
	ds_read_b64_tr_b16 v[178:179], v181 offset:0x440
	v_mfma_f32_16x16x32_bf16 v[144:147], v[184:187], v[172:175], v[144:147]
	ds_read_b64_tr_b16 v[184:185], v181 offset:32
	ds_read_b64_tr_b16 v[186:187], v181 offset:0x460
	ds_read_b64_tr_b16 v[188:189], v181 offset:64
	ds_read_b64_tr_b16 v[190:191], v181 offset:0x480
	v_mfma_f32_16x16x32_bf16 v[68:71], v[68:71], v[172:175], v[148:151]
	ds_read_b64_tr_b16 v[148:149], v181 offset:0x60
	ds_read_b64_tr_b16 v[150:151], v181 offset:0x4a0
	v_cvt_pk_bf16_f32 v196, v196, v197
	v_mfma_f32_16x16x32_bf16 v[64:67], v[64:67], v[172:175], v[152:155]
	ds_read_b64_tr_b16 v[152:153], v181 offset:0x80
	ds_read_b64_tr_b16 v[154:155], v181 offset:0x4c0
	ds_read_b64_tr_b16 v[192:193], v181 offset:0xa0
	ds_read_b64_tr_b16 v[194:195], v181 offset:0x4e0
	v_mfma_f32_16x16x32_bf16 v[60:63], v[60:63], v[172:175], v[156:159]
	ds_read_b64_tr_b16 v[156:157], v181 offset:0xc0
	ds_read_b64_tr_b16 v[158:159], v181 offset:0x500
	v_cvt_pk_bf16_f32 v197, v198, v199
	v_mfma_f32_16x16x32_bf16 v[56:59], v[56:59], v[172:175], v[160:163]
	ds_read_b64_tr_b16 v[160:161], v181 offset:0xe0
	ds_read_b64_tr_b16 v[162:163], v181 offset:0x520
	s_waitcnt lgkmcnt(0)
	v_mfma_f32_16x16x32_bf16 v[48:51], v[48:51], v[172:175], v[168:171]
	v_cvt_pk_bf16_f32 v198, v200, v201
	v_cvt_pk_bf16_f32 v199, v202, v203
	v_mfma_f32_16x16x32_bf16 v[52:55], v[52:55], v[172:175], v[164:167]
	v_add_u32_e32 v181, s41, v88
	ds_read_b64_tr_b16 v[164:165], v181 offset:0
	ds_read_b64_tr_b16 v[166:167], v181 offset:0x440
	ds_read_b64_tr_b16 v[168:169], v181 offset:32
	ds_read_b64_tr_b16 v[170:171], v181 offset:0x460
	ds_read_b64_tr_b16 v[172:173], v181 offset:64
	ds_read_b64_tr_b16 v[174:175], v181 offset:0x480
	v_mfma_f32_16x16x32_bf16 v[140:143], v[176:179], v[196:199], v[140:143]
	ds_read_b64_tr_b16 v[176:177], v181 offset:0x60
	ds_read_b64_tr_b16 v[178:179], v181 offset:0x4a0
	v_mfma_f32_16x16x32_bf16 v[64:67], v[148:151], v[196:199], v[64:67]
	ds_read_b64_tr_b16 v[148:149], v181 offset:0x80
	ds_read_b64_tr_b16 v[150:151], v181 offset:0x4c0
	v_mfma_f32_16x16x32_bf16 v[144:147], v[184:187], v[196:199], v[144:147]
	ds_read_b64_tr_b16 v[184:185], v181 offset:0xa0
	ds_read_b64_tr_b16 v[186:187], v181 offset:0x4e0
	v_mfma_f32_16x16x32_bf16 v[60:63], v[152:155], v[196:199], v[60:63]
	ds_read_b64_tr_b16 v[152:153], v181 offset:0xc0
	ds_read_b64_tr_b16 v[154:155], v181 offset:0x500
	v_mfma_f32_16x16x32_bf16 v[68:71], v[188:191], v[196:199], v[68:71]
	ds_read_b64_tr_b16 v[188:189], v181 offset:0xe0
	ds_read_b64_tr_b16 v[190:191], v181 offset:0x520
	s_waitcnt lgkmcnt(0)
	v_mfma_f32_16x16x32_bf16 v[48:51], v[160:163], v[196:199], v[48:51]
	v_mfma_f32_16x16x32_bf16 v[56:59], v[192:195], v[196:199], v[56:59]
	v_cvt_pk_bf16_f32 v192, v204, v205
	v_cvt_pk_bf16_f32 v193, v206, v207
	v_cvt_pk_bf16_f32 v194, v208, v209
	v_mfma_f32_16x16x32_bf16 v[52:55], v[156:159], v[196:199], v[52:55]
	v_cvt_pk_bf16_f32 v195, v210, v211
	v_add_u32_e32 v181, s40, v88
	ds_read_b64_tr_b16 v[156:157], v181 offset:0
	ds_read_b64_tr_b16 v[158:159], v181 offset:0x440
	ds_read_b64_tr_b16 v[160:161], v181 offset:32
	ds_read_b64_tr_b16 v[162:163], v181 offset:0x460
	s_nop 0
	v_mfma_f32_16x16x32_bf16 v[140:143], v[164:167], v[192:195], v[140:143]
	ds_read_b64_tr_b16 v[164:165], v181 offset:64
	ds_read_b64_tr_b16 v[166:167], v181 offset:0x480
	v_mfma_f32_16x16x32_bf16 v[144:147], v[168:171], v[192:195], v[144:147]
	ds_read_b64_tr_b16 v[168:169], v181 offset:0x60
	ds_read_b64_tr_b16 v[170:171], v181 offset:0x4a0
	v_mfma_f32_16x16x32_bf16 v[60:63], v[148:151], v[192:195], v[60:63]
	ds_read_b64_tr_b16 v[148:149], v181 offset:0x80
	ds_read_b64_tr_b16 v[150:151], v181 offset:0x4c0
	v_mfma_f32_16x16x32_bf16 v[68:71], v[172:175], v[192:195], v[68:71]
	ds_read_b64_tr_b16 v[172:173], v181 offset:0xa0
	ds_read_b64_tr_b16 v[174:175], v181 offset:0x4e0
	v_mfma_f32_16x16x32_bf16 v[64:67], v[176:179], v[192:195], v[64:67]
	ds_read_b64_tr_b16 v[176:177], v181 offset:0xc0
	ds_read_b64_tr_b16 v[178:179], v181 offset:0x500
	v_mfma_f32_16x16x32_bf16 v[52:55], v[152:155], v[192:195], v[52:55]
	ds_read_b64_tr_b16 v[152:153], v181 offset:0xe0
	ds_read_b64_tr_b16 v[154:155], v181 offset:0x520
	s_waitcnt lgkmcnt(0)
	v_mfma_f32_16x16x32_bf16 v[56:59], v[184:187], v[192:195], v[56:59]
	v_mfma_f32_16x16x32_bf16 v[184:187], v[188:191], v[192:195], v[48:51]
	v_cvt_pk_bf16_f32 v132, v132, v133
	v_cvt_pk_bf16_f32 v133, v134, v135
	v_cvt_pk_bf16_f32 v134, v136, v137
	v_cvt_pk_bf16_f32 v135, v138, v139
	v_add_u32_e32 v48, s96, v129
	v_ashrrev_i32_e32 v49, 31, v48
	v_mfma_f32_16x16x32_bf16 v[136:139], v[156:159], v[132:135], v[140:143]
	v_rcp_f32_e32 v156, v131
	v_lshl_add_u64 v[48:49], s[44:45], 0, v[48:49]
	v_lshlrev_b64 v[50:51], 11, v[48:49]
	v_mfma_f32_16x16x32_bf16 v[140:143], v[160:163], v[132:135], v[144:147]
	v_mfma_f32_16x16x32_bf16 v[68:71], v[164:167], v[132:135], v[68:71]
	s_nop 1
	v_lshl_add_u64 v[144:145], v[78:79], 0, v[50:51]
	v_pk_mul_f32 v[50:51], v[156:157], v[136:137] op_sel_hi:[0,1]
	v_pk_mul_f32 v[136:137], v[156:157], v[138:139] op_sel_hi:[0,1]
	v_cvt_pk_bf16_f32 v50, v50, v51
	v_cvt_pk_bf16_f32 v51, v136, v137
	v_mfma_f32_16x16x32_bf16 v[64:67], v[168:171], v[132:135], v[64:67]
	global_store_dwordx2 v[144:145], v[50:51], off nt
	v_pk_mul_f32 v[50:51], v[156:157], v[140:141] op_sel_hi:[0,1]
	v_pk_mul_f32 v[136:137], v[156:157], v[142:143] op_sel_hi:[0,1]
	v_cvt_pk_bf16_f32 v50, v50, v51
	v_cvt_pk_bf16_f32 v51, v136, v137
	v_mfma_f32_16x16x32_bf16 v[60:63], v[148:151], v[132:135], v[60:63]
	global_store_dwordx2 v[144:145], v[50:51], off offset:32 nt
	v_pk_mul_f32 v[136:137], v[156:157], v[70:71] op_sel_hi:[0,1]
	v_mfma_f32_16x16x32_bf16 v[50:53], v[176:179], v[132:135], v[52:55]
	s_nop 2
	v_mul_f32_e64 v54, v156, v68
	v_mul_f32_e64 v55, v156, v69
	v_cvt_pk_bf16_f32 v54, v54, v55
	v_cvt_pk_bf16_f32 v55, v136, v137
	v_mfma_f32_16x16x32_bf16 v[56:59], v[172:175], v[132:135], v[56:59]
	global_store_dwordx2 v[144:145], v[54:55], off offset:64 nt
	v_pk_mul_f32 v[54:55], v[156:157], v[64:65] op_sel_hi:[0,1]
	v_pk_mul_f32 v[64:65], v[156:157], v[66:67] op_sel_hi:[0,1]
	v_mfma_f32_16x16x32_bf16 v[68:71], v[152:155], v[132:135], v[184:187]
	v_cvt_pk_bf16_f32 v54, v54, v55
	v_cvt_pk_bf16_f32 v55, v64, v65
	global_store_dwordx2 v[144:145], v[54:55], off offset:96 nt
	v_pk_mul_f32 v[54:55], v[156:157], v[60:61] op_sel_hi:[0,1]
	v_pk_mul_f32 v[60:61], v[156:157], v[62:63] op_sel_hi:[0,1]
	v_pk_mul_f32 v[50:51], v[156:157], v[50:51] op_sel_hi:[0,1]
	v_pk_mul_f32 v[52:53], v[156:157], v[52:53] op_sel_hi:[0,1]
	v_cvt_pk_bf16_f32 v54, v54, v55
	v_cvt_pk_bf16_f32 v55, v60, v61
	v_cvt_pk_bf16_f32 v50, v50, v51
	v_cvt_pk_bf16_f32 v51, v52, v53
	global_store_dwordx2 v[144:145], v[54:55], off offset:128 nt
	v_pk_mul_f32 v[54:55], v[156:157], v[56:57] op_sel_hi:[0,1]
	v_pk_mul_f32 v[56:57], v[156:157], v[58:59] op_sel_hi:[0,1]
	global_store_dwordx2 v[144:145], v[50:51], off offset:192 nt
	v_pk_mul_f32 v[50:51], v[156:157], v[68:69] op_sel_hi:[0,1]
	v_pk_mul_f32 v[52:53], v[156:157], v[70:71] op_sel_hi:[0,1]
	v_cvt_pk_bf16_f32 v54, v54, v55
	v_cvt_pk_bf16_f32 v55, v56, v57
	v_cvt_pk_bf16_f32 v50, v50, v51
	v_cvt_pk_bf16_f32 v51, v52, v53
	global_store_dwordx2 v[144:145], v[54:55], off offset:160 nt
	global_store_dwordx2 v[144:145], v[50:51], off offset:224 nt
	s_and_saveexec_b64 s[40:41], s[4:5]
	s_cbranch_execz .LBB0_416
	v_log_f32_e32 v50, v131
	v_lshlrev_b64 v[48:49], 5, v[48:49]
	v_lshl_add_u64 v[48:49], s[84:85], 0, v[48:49]
	v_add_f32_e32 v50, v130, v50
	v_mul_f32_e32 v50, 0x3f317218, v50
	global_store_dword v[48:49], v50, off
